# NA tile loop: precomputed per-lane load offsets, scalar bases, saddr loads
# speedup vs baseline: 1.0002x; 1.0002x over previous
.LBB0_389:
	global_load_dword v7, v[2:3], off
	s_mov_b64 s[8:9], 0x400
	v_add_u32_e32 v6, 0x100, v6
	v_lshl_add_u64 v[2:3], v[2:3], 0, s[8:9]
	s_movk_i32 s8, 0xd0
	v_cmp_lt_u32_e32 vcc, s8, v6
	s_or_b64 s[4:5], vcc, s[4:5]
	s_waitcnt vmcnt(0)
	v_mul_f32_e32 v7, 0x3fb8aa3b, v7
	ds_write_b32 v5, v7
	v_add_u32_e32 v5, 0x400, v5
	s_andn2_b64 exec, exec, s[4:5]
	s_cbranch_execnz .LBB0_389
	s_or_b64 exec, exec, s[4:5]
	s_bfe_u32 s30, s35, 0x50003
	s_and_b32 s4, s6, 32
	s_or_b32 s48, s4, s30
	v_med3_u32 v2, s48, 4, 60
	s_lshr_b32 s82, s7, 8
	v_readfirstlane_b32 s4, v2
	s_mul_i32 s6, s4, 0x58000
	s_lshl_b64 s[4:5], s[82:83], 12
	s_add_u32 s71, s4, 0x1000
	s_addc_u32 s49, s5, 0
	s_mul_i32 s4, s49, 0x2c00
	s_mul_hi_u32 s5, s71, 0x2c00
	s_add_i32 s5, s5, s4
	s_mul_i32 s4, s71, 0x2c00
	s_add_u32 s4, s38, s4
	s_addc_u32 s5, s39, s5
	s_add_u32 s8, s4, 0x1e74b200
	s_addc_u32 s9, s5, 0
	s_add_i32 s4, s6, 0xffea0000
	s_mov_b32 s5, s83
	s_lshl_b64 s[4:5], s[4:5], 1
	s_add_u32 s4, s8, s4
	s_addc_u32 s5, s9, s5
	s_bfe_u32 s31, s34, 0x10008
	s_lshl_b32 s10, s31, 5
	s_lshl_b32 s6, s82, 2
	s_or_b32 s10, s10, s30
	s_add_i32 s82, s6, s96
	v_med3_u32 v2, s10, 4, 60
	s_movk_i32 s10, 0x7c
	v_lshlrev_b32_e32 v152, 7, v0
	s_lshl_b64 s[6:7], s[82:83], 18
	v_mul_lo_u32 v5, v2, s10
	s_mul_i32 s10, s48, 0xb0000
	s_add_u32 s8, s8, s10
	v_ashrrev_i32_e32 v153, 31, v152
	s_addc_u32 s9, s9, 0
	v_lshlrev_b64 v[2:3], 1, v[152:153]
	v_lshlrev_b64 v[0:1], 15, v[0:1]
	v_lshl_add_u64 v[6:7], s[8:9], 0, v[2:3]
	v_lshl_add_u64 v[2:3], s[4:5], 0, v[2:3]
	s_mov_b64 s[4:5], 0x1000
	v_lshl_add_u64 v[0:1], v[0:1], 0, s[6:7]
	v_lshl_add_u64 v[156:157], v[2:3], 0, s[4:5]
	v_lshl_add_u64 v[0:1], v[0:1], 1, s[38:39]
	s_mov_b64 s[4:5], 0x11a04000
	v_lshl_add_u64 v[158:159], v[0:1], 0, s[4:5]
	s_mov_b64 s[4:5], 0x11e04000
	v_lshl_add_u64 v[160:161], v[0:1], 0, s[4:5]
	v_lshrrev_b32_e32 v0, 2, v167
	v_and_b32_e32 v1, 15, v167
	v_and_b32_e32 v26, 48, v0
	v_or_b32_e32 v172, v26, v1
	v_mul_u32_u24_e32 v10, 0x1600, v172
	v_and_b32_e32 v17, 3, v171
	v_lshlrev_b32_e32 v10, 1, v10
	v_mov_b32_e32 v11, v16
	v_lshl_add_u64 v[6:7], v[6:7], 0, v[10:11]
	v_lshlrev_b32_e32 v10, 4, v17
	v_or_b32_e32 v214, 48, v171
	v_lshl_add_u64 v[6:7], v[6:7], 0, v[10:11]
	v_lshlrev_b32_e32 v27, 3, v169
	global_load_dwordx4 v[50:53], v[6:7], off offset:192
	global_load_dwordx4 v[54:57], v[6:7], off offset:128
	global_load_dwordx4 v[58:61], v[6:7], off offset:64
	global_load_dwordx4 v[62:65], v[6:7], off
	v_mul_u32_u24_e32 v6, 0x1600, v214
	v_mov_b32_e32 v7, v16
	s_movk_i32 s6, 0x1600
	v_mov_b32_e32 v11, 0xfffea000
	v_and_b32_e32 v8, 0x78, v27
	v_lshlrev_b64 v[6:7], 1, v[6:7]
	v_mad_u32_u24 v18, v214, s6, v11
	v_mov_b32_e32 v19, v16
	v_lshl_add_u64 v[12:13], v[156:157], 0, v[6:7]
	v_lshlrev_b32_e32 v14, 1, v8
	v_mov_b32_e32 v15, v16
	v_lshlrev_b64 v[18:19], 1, v[18:19]
	v_lshl_add_u64 v[12:13], v[12:13], 0, v[14:15]
	v_lshl_add_u64 v[20:21], v[156:157], 0, v[18:19]
	v_mov_b32_e32 v11, 0xfffd4000
	v_lshl_add_u64 v[20:21], v[20:21], 0, v[14:15]
	global_load_dwordx4 v[66:69], v[12:13], off
	global_load_dwordx4 v[70:73], v[20:21], off
	v_mad_u32_u24 v12, v214, s6, v11
	v_mov_b32_e32 v13, v16
	v_lshlrev_b64 v[12:13], 1, v[12:13]
	v_mul_u32_u24_e32 v22, 0x1600, v171
	v_mov_b32_e32 v23, v16
	v_lshl_add_u64 v[20:21], v[156:157], 0, v[12:13]
	v_lshlrev_b64 v[22:23], 1, v[22:23]
	v_lshl_add_u64 v[6:7], v[2:3], 0, v[6:7]
	v_lshl_add_u64 v[20:21], v[20:21], 0, v[14:15]
	v_lshl_add_u64 v[24:25], v[156:157], 0, v[22:23]
	v_lshl_add_u64 v[6:7], v[6:7], 0, v[14:15]
	v_lshl_add_u64 v[18:19], v[2:3], 0, v[18:19]
	v_lshl_add_u64 v[24:25], v[24:25], 0, v[14:15]
	global_load_dwordx4 v[74:77], v[20:21], off
	global_load_dwordx4 v[78:81], v[24:25], off
	v_lshl_add_u64 v[18:19], v[18:19], 0, v[14:15]
	global_load_dwordx4 v[86:89], v[6:7], off offset:2048
	global_load_dwordx4 v[94:97], v[18:19], off offset:2048
	v_lshl_add_u64 v[6:7], v[2:3], 0, v[12:13]
	v_lshl_add_u64 v[154:155], v[2:3], 0, s[94:95]
	v_lshl_add_u64 v[6:7], v[6:7], 0, v[14:15]
	v_lshl_add_u64 v[2:3], v[2:3], 0, v[22:23]
	v_lshlrev_b32_e32 v12, 4, v1
	v_mov_b32_e32 v13, v16
	v_lshl_add_u64 v[2:3], v[2:3], 0, v[12:13]
	global_load_dwordx4 v[82:85], v[6:7], off offset:2048
	global_load_dwordx4 v[90:93], v[2:3], off offset:2048
	v_and_b32_e32 v23, 64, v191
	v_xor_b32_e32 v22, 16, v191
	v_add_u32_e32 v23, 64, v23
	v_cmp_lt_i32_e32 vcc, v22, v23
	v_add_u32_e32 v9, 0, v4
	v_or_b32_e32 v182, 16, v171
	v_cndmask_b32_e32 v22, v191, v22, vcc
	v_or_b32_e32 v183, 32, v171
	v_lshlrev_b32_e32 v173, 2, v17
	v_and_b32_e32 v15, 24, v27
	v_lshlrev_b32_e32 v178, 2, v22
	v_xor_b32_e32 v22, 32, v191
	v_bitop3_b32 v24, v17, v1, 4 bitop3:0x36
	v_bitop3_b32 v17, v17, v1, 8 bitop3:0x36
	v_lshl_add_u32 v2, v171, 8, v9
	v_lshl_add_u32 v6, v182, 8, v9
	v_lshl_add_u32 v11, v183, 8, v9
	v_lshl_add_u32 v12, v214, 8, v9
	v_mad_u32_u24 v215, v171, s92, v9
	v_bfe_u32 v14, v167, 2, 2
	v_cmp_lt_i32_e32 vcc, v22, v23
	v_lshl_add_u32 v23, v1, 8, v9
	v_lshlrev_b32_e32 v25, 4, v17
	v_bitop3_b32 v17, v171, v1, 12 bitop3:0x36
	v_add_u32_e32 v9, v9, v15
	v_or_b32_e32 v15, 32, v173
	v_or_b32_e32 v28, 7, v26
	v_med3_u32 v20, v172, 8, 56
	v_lshlrev_b32_e32 v27, 4, v17
	v_or_b32_e32 v17, v173, v14
	v_or_b32_e32 v14, v15, v14
	v_add_u32_e32 v21, -8, v20
	v_cmp_lt_u32_e64 s[10:11], 16, v28
	v_cmp_lt_u32_e64 s[12:13], 32, v28
	v_mul_u32_u24_e32 v28, 0x120, v14
	v_or_b32_e32 v14, 1, v173
	v_cmp_ge_u32_e64 s[16:17], v14, v21
	v_or_b32_e32 v14, 2, v173
	v_cmp_ge_u32_e64 s[18:19], v14, v21
	v_or_b32_e32 v14, 3, v173
	v_add_u32_e32 v20, 8, v20
	v_cmp_ge_u32_e64 s[20:21], v14, v21
	v_or_b32_e32 v14, 16, v173
	v_cndmask_b32_e32 v22, v191, v22, vcc
	v_cmp_ge_u32_e32 vcc, v14, v21
	v_cmp_lt_u32_e64 s[22:23], v14, v20
	v_or_b32_e32 v14, 17, v173
	s_and_b64 s[52:53], vcc, s[22:23]
	v_cmp_ge_u32_e32 vcc, v14, v21
	v_cmp_lt_u32_e64 s[22:23], v14, v20
	v_or_b32_e32 v14, 18, v173
	s_and_b64 s[94:95], vcc, s[22:23]
	v_cmp_ge_u32_e32 vcc, v14, v21
	v_cmp_lt_u32_e64 s[22:23], v14, v20
	v_or_b32_e32 v14, 19, v173
	s_and_b64 s[76:77], vcc, s[22:23]
	v_cmp_ge_u32_e32 vcc, v14, v21
	v_cmp_lt_u32_e64 s[22:23], v14, v20
	s_and_b64 s[60:61], vcc, s[22:23]
	v_cmp_ge_u32_e32 vcc, v15, v21
	v_cmp_lt_u32_e64 s[22:23], v15, v20
	v_or_b32_e32 v14, 33, v173
	s_and_b64 s[62:63], vcc, s[22:23]
	v_cmp_ge_u32_e32 vcc, v14, v21
	v_cmp_lt_u32_e64 s[22:23], v14, v20
	v_or_b32_e32 v14, 34, v173
	s_and_b64 s[68:69], vcc, s[22:23]
	v_cmp_ge_u32_e32 vcc, v14, v21
	v_cmp_lt_u32_e64 s[22:23], v14, v20
	v_or_b32_e32 v14, 35, v173
	v_lshlrev_b32_e32 v0, 3, v1
	v_lshlrev_b32_e32 v179, 2, v22
	v_bitop3_b32 v22, v171, v1, 3 bitop3:0x6c
	s_and_b64 s[92:93], vcc, s[22:23]
	v_cmp_ge_u32_e32 vcc, v14, v21
	v_cmp_lt_u32_e64 s[22:23], v14, v20
	v_or_b32_e32 v14, 48, v173
	v_add3_u32 v4, v4, v5, v10
	v_lshlrev_b32_e32 v1, 2, v1
	s_and_b64 s[96:97], vcc, s[22:23]
	v_cmp_lt_u32_e64 s[22:23], v14, v20
	v_or_b32_e32 v14, 49, v173
	v_sub_u32_e32 v1, v4, v1
	v_and_b32_e32 v4, 0xc0, v167
	s_mulk_i32 s30, 0x7c
	v_xor_b32_e32 v7, v171, v169
	v_lshlrev_b32_e32 v13, 4, v169
	v_cmp_lt_u32_e64 s[24:25], v14, v20
	v_or_b32_e32 v14, 50, v173
	v_sub_u32_e32 v1, v1, v4
	s_mulk_i32 s31, 0xf80
	v_bitop3_b32 v3, v171, v167, 15 bitop3:0x78
	v_lshlrev_b32_e32 v7, 4, v7
	v_and_b32_e32 v216, 0xf0, v13
	v_add_u32_e32 v18, 0x2400, v215
	v_add_u32_e32 v19, 0x3600, v215
	v_lshlrev_b32_e32 v22, 4, v22
	v_lshlrev_b32_e32 v24, 4, v24
	v_cmp_gt_u32_e64 s[6:7], 17, v26
	v_cmp_gt_u32_e64 s[8:9], 33, v26
	v_mul_u32_u24_e32 v26, 0x120, v17
	v_cmp_lt_u32_e64 s[26:27], v14, v20
	v_or_b32_e32 v14, 51, v173
	v_subrev_u32_e32 v1, s30, v1
	v_mov_b32_e32 v17, v16
	v_lshlrev_b32_e32 v3, 4, v3
	v_and_b32_e32 v7, 0xf0, v7
	v_add_u32_e32 v13, 0x1200, v215
	v_cmp_ge_u32_e64 s[14:15], v173, v21
	v_cmp_lt_u32_e64 s[28:29], v14, v20
	v_subrev_u32_e32 v1, s31, v1
	v_readlane_b32 s30, v255, 12
	v_mov_b32_e32 v14, v16
	v_mov_b32_e32 v15, v16
	v_add_u32_e32 v223, v18, v216
	v_add_u32_e32 v224, v19, v216
	v_add_u32_e32 v220, v23, v22
	v_add_u32_e32 v219, v23, v24
	v_add_u32_e32 v218, v23, v25
	v_add_u32_e32 v217, v23, v27
	v_add_u32_e32 v181, v9, v26
	v_add_u32_e32 v180, v9, v28
	v_mov_b64_e32 v[48:49], v[16:17]
	v_mov_b64_e32 v[44:45], v[16:17]
	v_mov_b64_e32 v[40:41], v[16:17]
	v_mov_b64_e32 v[36:37], v[16:17]
	v_mov_b64_e32 v[32:33], v[16:17]
	v_mov_b64_e32 v[28:29], v[16:17]
	v_mov_b64_e32 v[24:25], v[16:17]
	v_mov_b64_e32 v[20:21], v[16:17]
	v_cmp_gt_u32_e64 s[4:5], 64, v169
	s_mov_b32 s82, 0
	v_add_u32_e32 v221, s30, v1
	v_mov_b32_e32 v230, 0xf149f2ca
	v_mov_b32_e32 v229, 0
	v_lshlrev_b32_e32 v162, 1, v0
	v_lshlrev_b32_e32 v164, 1, v8
	v_add_u32_e32 v225, v2, v3
	v_add_u32_e32 v226, v6, v7
	v_add_u32_e32 v227, v11, v7
	v_add_u32_e32 v228, v12, v7
	v_add_u32_e32 v222, v13, v216
	v_mov_b64_e32 v[46:47], v[14:15]
	v_mov_b64_e32 v[42:43], v[14:15]
	v_mov_b64_e32 v[38:39], v[14:15]
	v_mov_b64_e32 v[34:35], v[14:15]
	v_mov_b64_e32 v[30:31], v[14:15]
	v_mov_b64_e32 v[26:27], v[14:15]
	v_mov_b64_e32 v[22:23], v[14:15]
	v_mov_b64_e32 v[18:19], v[14:15]
	s_movk_i32 s66, 0x2c00
	v_mad_u32_u24 v236, v171, s66, v162
	v_mad_u32_u24 v237, v171, s66, v164
	v_mad_u32_u24 v238, v182, s66, v164
	v_mad_u32_u24 v239, v183, s66, v164
	v_mad_u32_u24 v240, v214, s66, v164
	v_lshl_add_u32 v241, v171, 8, v162
	v_lshl_add_u32 v242, v171, 8, v164
	v_lshl_add_u32 v243, v182, 8, v164
	v_lshl_add_u32 v244, v183, 8, v164
	v_lshl_add_u32 v245, v214, 8, v164
.LBB0_391:
	s_cmp_lt_u32 s82, 7
	s_cbranch_scc0 .Lna_ctx1
	s_add_i32 s66, s82, 1
	s_mul_i32 s66, s66, 0xb0000
	v_readfirstlane_b32 s98, v154
	v_readfirstlane_b32 s99, v155
	v_readfirstlane_b32 s100, v156
	v_readfirstlane_b32 s101, v157
	s_branch .Lna_iss1
.Lna_ctx1:
	s_add_i32 s66, s82, -7
	s_lshl_b32 s66, s66, 14
	v_readfirstlane_b32 s98, v158
	v_readfirstlane_b32 s99, v159
	v_readfirstlane_b32 s100, v160
	v_readfirstlane_b32 s101, v161
.Lna_iss1:
	s_add_u32 s98, s98, s66
	s_addc_u32 s99, s99, 0
	s_add_u32 s100, s100, s66
	s_addc_u32 s101, s101, 0
	v_add_u32_e32 v17, v215, v216
	s_waitcnt lgkmcnt(0)
	s_barrier
	s_waitcnt vmcnt(0)
	ds_write_b128 v225, v[90:93]
	ds_write_b128 v226, v[82:85]
	ds_write_b128 v227, v[94:97]
	ds_write_b128 v228, v[86:89]
	ds_write_b128 v17, v[78:81] offset:16384
	ds_write_b128 v222, v[74:77] offset:16384
	ds_write_b128 v223, v[70:73] offset:16384
	ds_write_b128 v224, v[66:69] offset:16384
	s_waitcnt lgkmcnt(0)
	s_barrier
	s_cmp_lt_u32 s82, 7
	s_cbranch_scc0 .Lna_ctx2
	global_load_dwordx4 v[90:93], v236, s[98:99]
	global_load_dwordx4 v[82:85], v238, s[98:99]
	global_load_dwordx4 v[94:97], v239, s[98:99]
	global_load_dwordx4 v[86:89], v240, s[98:99]
	global_load_dwordx4 v[78:81], v237, s[100:101]
	global_load_dwordx4 v[74:77], v238, s[100:101]
	global_load_dwordx4 v[70:73], v239, s[100:101]
	global_load_dwordx4 v[66:69], v240, s[100:101]
	s_branch .Lna_iss2
.Lna_ctx2:
	global_load_dwordx4 v[90:93], v241, s[98:99]
	global_load_dwordx4 v[82:85], v243, s[98:99]
	global_load_dwordx4 v[94:97], v244, s[98:99]
	global_load_dwordx4 v[86:89], v245, s[98:99]
	global_load_dwordx4 v[78:81], v242, s[100:101]
	global_load_dwordx4 v[74:77], v243, s[100:101]
	global_load_dwordx4 v[70:73], v244, s[100:101]
	global_load_dwordx4 v[66:69], v245, s[100:101]
.Lna_iss2:
	ds_read_b128 v[4:7], v220
	ds_read_b128 v[8:11], v220 offset:4096
	ds_read_b128 v[138:141], v219
	ds_read_b128 v[12:15], v219 offset:4096
	ds_read_b128 v[142:145], v218
	ds_read_b128 v[130:133], v218 offset:4096
	ds_read_b128 v[146:149], v217
	ds_read_b128 v[134:137], v217 offset:4096
	ds_read_b128 v[114:117], v220 offset:8192
	ds_read_b128 v[98:101], v220 offset:12288
	ds_read_b128 v[118:121], v219 offset:8192
	ds_read_b128 v[102:105], v219 offset:12288
	ds_read_b128 v[122:125], v218 offset:8192
	ds_read_b128 v[106:109], v218 offset:12288
	ds_read_b128 v[126:129], v217 offset:8192
	ds_read_b128 v[110:113], v217 offset:12288
	s_cmp_gt_u32 s82, 7
	s_cselect_b64 s[30:31], -1, 0
	s_cmp_lt_u32 s82, 8
	s_cselect_b64 s[66:67], -1, 0
	s_or_b64 s[72:73], s[30:31], s[4:5]
	s_or_b64 s[90:91], s[72:73], s[6:7]
	v_mov_b32_e32 v0, 0
	v_mov_b32_e32 v1, 0
	v_mov_b32_e32 v2, 0
	v_mov_b32_e32 v3, 0
	s_and_saveexec_b64 vcc, s[90:91]
	s_cbranch_execz .LBB0_393
	s_waitcnt lgkmcnt(14)
	v_mfma_f32_16x16x32_bf16 v[0:3], v[4:7], v[62:65], 0
	s_waitcnt lgkmcnt(13)
	v_mfma_f32_16x16x32_bf16 v[0:3], v[138:141], v[58:61], v[0:3]
	s_waitcnt lgkmcnt(11)
	v_mfma_f32_16x16x32_bf16 v[0:3], v[142:145], v[54:57], v[0:3]
	s_waitcnt lgkmcnt(9)
	v_mfma_f32_16x16x32_bf16 v[0:3], v[146:149], v[50:53], v[0:3]
